# norm phases (P0b/P3/P12/final): parameter loads issued together per trip (final norm: weight hoisted out of the loop), straight-line tails; on the P5/P7 bundle
# speedup vs baseline: 1.0119x; 1.0119x over previous
.LBB0_209:
	v_ashrrev_i32_e32 v55, 31, v54
	v_add_u32_e32 v75, s94, v54
	v_lshlrev_b64 v[0:1], 12, v[54:55]
	v_cmp_gt_i32_e32 vcc, s2, v75
	v_lshl_add_u64 v[0:1], v[38:39], 0, v[0:1]
	global_load_dwordx4 v[28:31], v[0:1], off nt
	global_load_dwordx4 v[20:23], v[0:1], off offset:1024 nt
	global_load_dwordx4 v[4:7], v[0:1], off offset:3072 nt
	global_load_dwordx4 v[12:15], v[0:1], off offset:2048 nt
	v_cndmask_b32_e32 v56, v54, v75, vcc
	v_ashrrev_i32_e32 v57, 31, v56
	v_lshlrev_b64 v[0:1], 12, v[56:57]
	v_lshl_add_u64 v[32:33], v[38:39], 0, v[0:1]
	global_load_dwordx4 v[24:27], v[32:33], off nt
	global_load_dwordx4 v[16:19], v[32:33], off offset:1024 nt
	global_load_dwordx4 v[0:3], v[32:33], off offset:3072 nt
	global_load_dwordx4 v[8:11], v[32:33], off offset:2048 nt
	s_waitcnt vmcnt(7)
	v_pk_mul_f32 v[32:33], v[30:31], v[30:31]
	v_pk_mul_f32 v[34:35], v[28:29], v[28:29]
	s_waitcnt vmcnt(6)
	v_pk_mul_f32 v[58:59], v[22:23], v[22:23]
	v_pk_mul_f32 v[60:61], v[20:21], v[20:21]
	s_waitcnt vmcnt(4)
	v_mul_f32_e32 v62, v15, v15
	v_pk_mov_b32 v[64:65], v[34:35], v[32:33] op_sel:[1,0]
	v_mov_b32_e32 v35, v33
	v_pk_mov_b32 v[32:33], v[60:61], v[58:59] op_sel:[1,0]
	v_mov_b32_e32 v61, v59
	v_mul_f32_e32 v78, v7, v7
	v_mul_f32_e32 v36, v13, v13
	v_pk_fma_f32 v[62:63], v[14:15], v[14:15], v[62:63] op_sel_hi:[1,1,0]
	v_pk_add_f32 v[34:35], v[64:65], v[34:35]
	s_waitcnt vmcnt(3)
	v_pk_mul_f32 v[64:65], v[26:27], v[26:27]
	v_pk_mul_f32 v[66:67], v[24:25], v[24:25]
	v_pk_add_f32 v[32:33], v[32:33], v[60:61]
	s_waitcnt vmcnt(2)
	v_pk_mul_f32 v[60:61], v[18:19], v[18:19]
	v_pk_mul_f32 v[68:69], v[16:17], v[16:17]
	v_mul_f32_e32 v51, v4, v4
	v_mul_f32_e32 v77, v5, v5
	v_mul_f32_e32 v76, v6, v6
	v_pk_fma_f32 v[58:59], v[12:13], v[12:13], v[36:37] op_sel_hi:[1,1,0]
	v_mov_b32_e32 v63, v78
	v_pk_mov_b32 v[78:79], v[66:67], v[64:65] op_sel:[1,0]
	v_mov_b32_e32 v67, v65
	v_pk_mov_b32 v[64:65], v[68:69], v[60:61] op_sel:[1,0]
	v_mov_b32_e32 v69, v61
	v_pk_add_f32 v[34:35], v[34:35], v[34:35] op_sel:[0,1] op_sel_hi:[1,0]
	v_pk_add_f32 v[32:33], v[32:33], v[32:33] op_sel:[0,1] op_sel_hi:[1,0]
	v_mov_b32_e32 v59, v76
	s_waitcnt vmcnt(0)
	v_mul_f32_e32 v36, v9, v9
	v_mul_f32_e32 v76, v11, v11
	v_pk_add_f32 v[66:67], v[78:79], v[66:67]
	v_pk_add_f32 v[64:65], v[64:65], v[68:69]
	v_mov_b32_e32 v35, v51
	v_mov_b32_e32 v33, v77
	v_mul_f32_e32 v80, v0, v0
	v_mul_f32_e32 v81, v1, v1
	v_mul_f32_e32 v82, v2, v2
	v_mul_f32_e32 v83, v3, v3
	v_pk_add_f32 v[58:59], v[58:59], v[62:63]
	v_pk_fma_f32 v[60:61], v[8:9], v[8:9], v[36:37] op_sel_hi:[1,1,0]
	v_pk_fma_f32 v[62:63], v[10:11], v[10:11], v[76:77] op_sel_hi:[1,1,0]
	v_pk_add_f32 v[32:33], v[34:35], v[32:33]
	v_pk_add_f32 v[34:35], v[66:67], v[66:67] op_sel:[0,1] op_sel_hi:[1,0]
	v_pk_add_f32 v[64:65], v[64:65], v[64:65] op_sel:[0,1] op_sel_hi:[1,0]
	v_mov_b32_e32 v61, v82
	v_mov_b32_e32 v63, v83
	v_pk_add_f32 v[32:33], v[32:33], v[58:59]
	v_mov_b32_e32 v35, v80
	v_mov_b32_e32 v65, v81
	v_pk_add_f32 v[60:61], v[60:61], v[62:63]
	v_add_f32_e32 v36, v32, v33
	v_pk_add_f32 v[32:33], v[34:35], v[64:65]
	ds_bpermute_b32 v34, v45, v36
	v_pk_add_f32 v[32:33], v[32:33], v[60:61]
	v_ashrrev_i32_e32 v58, 12, v54
	v_add_f32_e32 v32, v32, v33
	ds_bpermute_b32 v33, v45, v32
	v_mul_hi_i32_i24_e32 v59, 0x9000, v58
	v_mul_i32_i24_e32 v58, 0x9000, v58
	s_waitcnt lgkmcnt(1)
	v_add_f32_e32 v36, v36, v34
	ds_bpermute_b32 v51, v47, v36
	s_waitcnt lgkmcnt(1)
	v_add_f32_e32 v60, v32, v33
	ds_bpermute_b32 v61, v47, v60
	global_load_dwordx4 v[32:35], v[42:43], off
	s_waitcnt lgkmcnt(1)
	v_add_f32_e32 v36, v36, v51
	ds_bpermute_b32 v51, v49, v36
	s_waitcnt lgkmcnt(1)
	v_add_f32_e32 v62, v60, v61
	ds_bpermute_b32 v63, v49, v62
	v_lshl_add_u64 v[60:61], s[8:9], 0, v[58:59]
	v_lshl_add_u64 v[58:59], v[60:61], 0, s[12:13]
	v_lshl_add_u64 v[60:61], v[60:61], 0, v[52:53]
	global_load_dwordx4 v[76:79], v[60:61], off
	s_waitcnt lgkmcnt(0)
	v_add_f32_e32 v62, v62, v63
	ds_bpermute_b32 v63, v70, v62
	v_add_f32_e32 v36, v36, v51
	ds_bpermute_b32 v51, v70, v36
	s_waitcnt lgkmcnt(1)
	v_add_f32_e32 v64, v62, v63
	v_lshl_add_u64 v[62:63], v[58:59], 0, v[52:53]
	global_load_dwordx4 v[80:83], v[62:63], off
	global_load_dwordx4 v[84:87], v[42:43], off offset:1024
	global_load_dwordx4 v[96:99], v[62:63], off offset:1024
	global_load_dwordx4 v[108:111], v[60:61], off offset:1024
	global_load_dwordx4 v[88:91], v[42:43], off offset:2048
	global_load_dwordx4 v[100:103], v[62:63], off offset:2048
	global_load_dwordx4 v[112:115], v[60:61], off offset:2048
	global_load_dwordx4 v[92:95], v[42:43], off offset:3072
	global_load_dwordx4 v[104:107], v[62:63], off offset:3072
	global_load_dwordx4 v[116:119], v[60:61], off offset:3072
	s_waitcnt lgkmcnt(0)
	v_add_f32_e32 v36, v36, v51
	ds_bpermute_b32 v51, v71, v36
	ds_bpermute_b32 v65, v71, v64
	s_waitcnt lgkmcnt(1)
	v_add_f32_e32 v36, v36, v51
	ds_bpermute_b32 v51, v72, v36
	s_waitcnt lgkmcnt(1)
	v_add_f32_e32 v64, v64, v65
	ds_bpermute_b32 v65, v72, v64
	s_waitcnt lgkmcnt(1)
	v_add_f32_e32 v36, v36, v51
	v_fmamk_f32 v36, v36, 0x3a800000, v73
	v_mul_f32_e32 v51, 0x4f800000, v36
	v_cmp_gt_f32_e32 vcc, s3, v36
	s_waitcnt lgkmcnt(0)
	v_add_f32_e32 v62, v64, v65
	v_cndmask_b32_e32 v36, v36, v51, vcc
	v_fmamk_f32 v51, v62, 0x3a800000, v73
	v_sqrt_f32_e32 v62, v36
	v_mul_f32_e32 v63, 0x4f800000, v51
	v_cmp_gt_f32_e64 s[4:5], s3, v51
	v_add_u32_e32 v64, -1, v62
	v_cndmask_b32_e64 v51, v51, v63, s[4:5]
	v_sqrt_f32_e32 v63, v51
	v_add_u32_e32 v65, 1, v62
	v_fma_f32 v66, -v64, v62, v36
	v_fma_f32 v67, -v65, v62, v36
	v_cmp_ge_f32_e64 s[6:7], 0, v66
	v_add_u32_e32 v66, 1, v63
	s_nop 0
	v_cndmask_b32_e64 v62, v62, v64, s[6:7]
	v_add_u32_e32 v64, -1, v63
	v_cmp_lt_f32_e64 s[6:7], 0, v67
	v_fma_f32 v67, -v66, v63, v51
	s_nop 0
	v_cndmask_b32_e64 v62, v62, v65, s[6:7]
	v_fma_f32 v65, -v64, v63, v51
	v_mul_f32_e32 v68, 0x37800000, v62
	v_cmp_ge_f32_e64 s[6:7], 0, v65
	v_cndmask_b32_e32 v62, v62, v68, vcc
	v_cmp_lt_f32_e32 vcc, 0, v67
	v_cndmask_b32_e64 v63, v63, v64, s[6:7]
	s_nop 0
	v_cndmask_b32_e32 v63, v63, v66, vcc
	v_cmp_class_f32_e32 vcc, v36, v74
	s_nop 1
	v_cndmask_b32_e32 v36, v62, v36, vcc
	v_div_scale_f32 v64, s[6:7], v36, v36, 1.0
	v_rcp_f32_e32 v66, v64
	v_mul_f32_e32 v62, 0x37800000, v63
	v_cndmask_b32_e64 v62, v63, v62, s[4:5]
	v_cmp_class_f32_e64 s[4:5], v51, v74
	v_div_scale_f32 v65, vcc, 1.0, v36, 1.0
	s_nop 0
	v_cndmask_b32_e64 v51, v62, v51, s[4:5]
	v_fma_f32 v62, -v64, v66, 1.0
	v_fmac_f32_e32 v66, v62, v66
	v_mul_f32_e32 v62, v65, v66
	v_fma_f32 v63, -v64, v62, v65
	v_fmac_f32_e32 v62, v63, v66
	v_fma_f32 v63, -v64, v62, v65
	v_div_scale_f32 v64, s[4:5], v51, v51, 1.0
	v_rcp_f32_e32 v65, v64
	v_div_fmas_f32 v62, v63, v66, v62
	v_div_fixup_f32 v68, v62, v36, 1.0
	v_fma_f32 v36, -v64, v65, 1.0
	v_fmac_f32_e32 v65, v36, v65
	v_div_scale_f32 v36, vcc, 1.0, v51, 1.0
	v_mul_f32_e32 v62, v36, v65
	v_fma_f32 v63, -v64, v62, v36
	v_fmac_f32_e32 v62, v63, v65
	v_fma_f32 v36, -v64, v62, v36
	v_div_fmas_f32 v36, v36, v65, v62
	v_div_fixup_f32 v64, v36, v51, 1.0
	v_lshlrev_b64 v[124:125], 11, v[54:55]
	v_lshlrev_b64 v[126:127], 11, v[56:57]
	v_mov_b32_e32 v120, v68
	v_mov_b32_e32 v122, v64
	v_lshl_add_u64 v[124:125], v[40:41], 0, v[124:125]
	v_lshl_add_u64 v[126:127], v[40:41], 0, v[126:127]
	s_waitcnt vmcnt(0)
	v_pk_add_f32 v[80:81], v[80:81], 1.0 op_sel_hi:[1,0]
	v_pk_add_f32 v[82:83], v[82:83], 1.0 op_sel_hi:[1,0]
	v_pk_mul_f32 v[28:29], v[28:29], v[120:121] op_sel_hi:[1,0]
	v_pk_mul_f32 v[30:31], v[30:31], v[120:121] op_sel_hi:[1,0]
	v_pk_mul_f32 v[28:29], v[32:33], v[28:29]
	v_pk_mul_f32 v[30:31], v[34:35], v[30:31]
	v_pk_fma_f32 v[28:29], v[80:81], v[28:29], v[76:77]
	v_pk_fma_f32 v[30:31], v[82:83], v[30:31], v[78:79]
	v_cvt_pk_bf16_f32 v28, v28, v29
	v_cvt_pk_bf16_f32 v29, v30, v31
	global_store_dwordx2 v[124:125], v[28:29], off
	v_pk_mul_f32 v[24:25], v[24:25], v[122:123] op_sel_hi:[1,0]
	v_pk_mul_f32 v[26:27], v[26:27], v[122:123] op_sel_hi:[1,0]
	v_pk_mul_f32 v[24:25], v[32:33], v[24:25]
	v_pk_mul_f32 v[26:27], v[34:35], v[26:27]
	v_pk_fma_f32 v[24:25], v[80:81], v[24:25], v[76:77]
	v_pk_fma_f32 v[26:27], v[82:83], v[26:27], v[78:79]
	v_cvt_pk_bf16_f32 v24, v24, v25
	v_cvt_pk_bf16_f32 v25, v26, v27
	global_store_dwordx2 v[126:127], v[24:25], off
	v_pk_add_f32 v[96:97], v[96:97], 1.0 op_sel_hi:[1,0]
	v_pk_add_f32 v[98:99], v[98:99], 1.0 op_sel_hi:[1,0]
	v_pk_mul_f32 v[20:21], v[20:21], v[120:121] op_sel_hi:[1,0]
	v_pk_mul_f32 v[22:23], v[22:23], v[120:121] op_sel_hi:[1,0]
	v_pk_mul_f32 v[20:21], v[84:85], v[20:21]
	v_pk_mul_f32 v[22:23], v[86:87], v[22:23]
	v_pk_fma_f32 v[20:21], v[96:97], v[20:21], v[108:109]
	v_pk_fma_f32 v[22:23], v[98:99], v[22:23], v[110:111]
	v_cvt_pk_bf16_f32 v20, v20, v21
	v_cvt_pk_bf16_f32 v21, v22, v23
	global_store_dwordx2 v[124:125], v[20:21], off offset:512
	v_pk_mul_f32 v[16:17], v[16:17], v[122:123] op_sel_hi:[1,0]
	v_pk_mul_f32 v[18:19], v[18:19], v[122:123] op_sel_hi:[1,0]
	v_pk_mul_f32 v[16:17], v[84:85], v[16:17]
	v_pk_mul_f32 v[18:19], v[86:87], v[18:19]
	v_pk_fma_f32 v[16:17], v[96:97], v[16:17], v[108:109]
	v_pk_fma_f32 v[18:19], v[98:99], v[18:19], v[110:111]
	v_cvt_pk_bf16_f32 v16, v16, v17
	v_cvt_pk_bf16_f32 v17, v18, v19
	global_store_dwordx2 v[126:127], v[16:17], off offset:512
	v_pk_add_f32 v[100:101], v[100:101], 1.0 op_sel_hi:[1,0]
	v_pk_add_f32 v[102:103], v[102:103], 1.0 op_sel_hi:[1,0]
	v_pk_mul_f32 v[12:13], v[12:13], v[120:121] op_sel_hi:[1,0]
	v_pk_mul_f32 v[14:15], v[14:15], v[120:121] op_sel_hi:[1,0]
	v_pk_mul_f32 v[12:13], v[88:89], v[12:13]
	v_pk_mul_f32 v[14:15], v[90:91], v[14:15]
	v_pk_fma_f32 v[12:13], v[100:101], v[12:13], v[112:113]
	v_pk_fma_f32 v[14:15], v[102:103], v[14:15], v[114:115]
	v_cvt_pk_bf16_f32 v12, v12, v13
	v_cvt_pk_bf16_f32 v13, v14, v15
	global_store_dwordx2 v[124:125], v[12:13], off offset:1024
	v_pk_mul_f32 v[8:9], v[8:9], v[122:123] op_sel_hi:[1,0]
	v_pk_mul_f32 v[10:11], v[10:11], v[122:123] op_sel_hi:[1,0]
	v_pk_mul_f32 v[8:9], v[88:89], v[8:9]
	v_pk_mul_f32 v[10:11], v[90:91], v[10:11]
	v_pk_fma_f32 v[8:9], v[100:101], v[8:9], v[112:113]
	v_pk_fma_f32 v[10:11], v[102:103], v[10:11], v[114:115]
	v_cvt_pk_bf16_f32 v8, v8, v9
	v_cvt_pk_bf16_f32 v9, v10, v11
	global_store_dwordx2 v[126:127], v[8:9], off offset:1024
	v_pk_add_f32 v[104:105], v[104:105], 1.0 op_sel_hi:[1,0]
	v_pk_add_f32 v[106:107], v[106:107], 1.0 op_sel_hi:[1,0]
	v_pk_mul_f32 v[4:5], v[4:5], v[120:121] op_sel_hi:[1,0]
	v_pk_mul_f32 v[6:7], v[6:7], v[120:121] op_sel_hi:[1,0]
	v_pk_mul_f32 v[4:5], v[92:93], v[4:5]
	v_pk_mul_f32 v[6:7], v[94:95], v[6:7]
	v_pk_fma_f32 v[4:5], v[104:105], v[4:5], v[116:117]
	v_pk_fma_f32 v[6:7], v[106:107], v[6:7], v[118:119]
	v_cvt_pk_bf16_f32 v4, v4, v5
	v_cvt_pk_bf16_f32 v5, v6, v7
	global_store_dwordx2 v[124:125], v[4:5], off offset:1536
	v_pk_mul_f32 v[0:1], v[0:1], v[122:123] op_sel_hi:[1,0]
	v_pk_mul_f32 v[2:3], v[2:3], v[122:123] op_sel_hi:[1,0]
	v_pk_mul_f32 v[0:1], v[92:93], v[0:1]
	v_pk_mul_f32 v[2:3], v[94:95], v[2:3]
	v_pk_fma_f32 v[0:1], v[104:105], v[0:1], v[116:117]
	v_pk_fma_f32 v[2:3], v[106:107], v[2:3], v[118:119]
	v_cvt_pk_bf16_f32 v0, v0, v1
	v_cvt_pk_bf16_f32 v1, v2, v3
	global_store_dwordx2 v[126:127], v[0:1], off offset:1536
	s_mov_b64 s[4:5], exec
	s_branch .LBB0_208

.LBB0_420:
	v_ashrrev_i32_e32 v55, 31, v54
	v_add_u32_e32 v75, s94, v54
	v_lshlrev_b64 v[0:1], 12, v[54:55]
	v_cmp_gt_i32_e32 vcc, s2, v75
	v_lshl_add_u64 v[0:1], v[38:39], 0, v[0:1]
	global_load_dwordx4 v[28:31], v[0:1], off nt
	global_load_dwordx4 v[20:23], v[0:1], off offset:1024 nt
	global_load_dwordx4 v[4:7], v[0:1], off offset:3072 nt
	global_load_dwordx4 v[12:15], v[0:1], off offset:2048 nt
	v_cndmask_b32_e32 v56, v54, v75, vcc
	v_ashrrev_i32_e32 v57, 31, v56
	v_lshlrev_b64 v[0:1], 12, v[56:57]
	v_lshl_add_u64 v[32:33], v[38:39], 0, v[0:1]
	global_load_dwordx4 v[24:27], v[32:33], off nt
	global_load_dwordx4 v[16:19], v[32:33], off offset:1024 nt
	global_load_dwordx4 v[0:3], v[32:33], off offset:3072 nt
	global_load_dwordx4 v[8:11], v[32:33], off offset:2048 nt
	s_waitcnt vmcnt(7)
	v_pk_mul_f32 v[32:33], v[30:31], v[30:31]
	v_pk_mul_f32 v[34:35], v[28:29], v[28:29]
	s_waitcnt vmcnt(6)
	v_pk_mul_f32 v[58:59], v[22:23], v[22:23]
	v_pk_mul_f32 v[60:61], v[20:21], v[20:21]
	s_waitcnt vmcnt(4)
	v_mul_f32_e32 v62, v15, v15
	v_pk_mov_b32 v[64:65], v[34:35], v[32:33] op_sel:[1,0]
	v_mov_b32_e32 v35, v33
	v_pk_mov_b32 v[32:33], v[60:61], v[58:59] op_sel:[1,0]
	v_mov_b32_e32 v61, v59
	v_mul_f32_e32 v78, v7, v7
	v_mul_f32_e32 v36, v13, v13
	v_pk_fma_f32 v[62:63], v[14:15], v[14:15], v[62:63] op_sel_hi:[1,1,0]
	v_pk_add_f32 v[34:35], v[64:65], v[34:35]
	s_waitcnt vmcnt(3)
	v_pk_mul_f32 v[64:65], v[26:27], v[26:27]
	v_pk_mul_f32 v[66:67], v[24:25], v[24:25]
	v_pk_add_f32 v[32:33], v[32:33], v[60:61]
	s_waitcnt vmcnt(2)
	v_pk_mul_f32 v[60:61], v[18:19], v[18:19]
	v_pk_mul_f32 v[68:69], v[16:17], v[16:17]
	v_mul_f32_e32 v51, v4, v4
	v_mul_f32_e32 v77, v5, v5
	v_mul_f32_e32 v76, v6, v6
	v_pk_fma_f32 v[58:59], v[12:13], v[12:13], v[36:37] op_sel_hi:[1,1,0]
	v_mov_b32_e32 v63, v78
	v_pk_mov_b32 v[78:79], v[66:67], v[64:65] op_sel:[1,0]
	v_mov_b32_e32 v67, v65
	v_pk_mov_b32 v[64:65], v[68:69], v[60:61] op_sel:[1,0]
	v_mov_b32_e32 v69, v61
	v_pk_add_f32 v[34:35], v[34:35], v[34:35] op_sel:[0,1] op_sel_hi:[1,0]
	v_pk_add_f32 v[32:33], v[32:33], v[32:33] op_sel:[0,1] op_sel_hi:[1,0]
	v_mov_b32_e32 v59, v76
	s_waitcnt vmcnt(0)
	v_mul_f32_e32 v36, v9, v9
	v_mul_f32_e32 v76, v11, v11
	v_pk_add_f32 v[66:67], v[78:79], v[66:67]
	v_pk_add_f32 v[64:65], v[64:65], v[68:69]
	v_mov_b32_e32 v35, v51
	v_mov_b32_e32 v33, v77
	v_mul_f32_e32 v80, v0, v0
	v_mul_f32_e32 v81, v1, v1
	v_mul_f32_e32 v82, v2, v2
	v_mul_f32_e32 v83, v3, v3
	v_pk_add_f32 v[58:59], v[58:59], v[62:63]
	v_pk_fma_f32 v[60:61], v[8:9], v[8:9], v[36:37] op_sel_hi:[1,1,0]
	v_pk_fma_f32 v[62:63], v[10:11], v[10:11], v[76:77] op_sel_hi:[1,1,0]
	v_pk_add_f32 v[32:33], v[34:35], v[32:33]
	v_pk_add_f32 v[34:35], v[66:67], v[66:67] op_sel:[0,1] op_sel_hi:[1,0]
	v_pk_add_f32 v[64:65], v[64:65], v[64:65] op_sel:[0,1] op_sel_hi:[1,0]
	v_mov_b32_e32 v61, v82
	v_mov_b32_e32 v63, v83
	v_pk_add_f32 v[32:33], v[32:33], v[58:59]
	v_mov_b32_e32 v35, v80
	v_mov_b32_e32 v65, v81
	v_pk_add_f32 v[60:61], v[60:61], v[62:63]
	v_add_f32_e32 v36, v32, v33
	v_pk_add_f32 v[32:33], v[34:35], v[64:65]
	ds_bpermute_b32 v34, v45, v36
	v_pk_add_f32 v[32:33], v[32:33], v[60:61]
	v_ashrrev_i32_e32 v51, 12, v54
	v_add_f32_e32 v32, v32, v33
	ds_bpermute_b32 v33, v45, v32
	s_waitcnt lgkmcnt(1)
	v_add_f32_e32 v36, v36, v34
	ds_bpermute_b32 v58, v47, v36
	v_mul_hi_i32_i24_e32 v59, 0x9000, v51
	s_waitcnt lgkmcnt(1)
	v_add_f32_e32 v60, v32, v33
	ds_bpermute_b32 v61, v47, v60
	s_waitcnt lgkmcnt(1)
	v_add_f32_e32 v36, v36, v58
	ds_bpermute_b32 v62, v49, v36
	v_mul_i32_i24_e32 v58, 0x9000, v51
	v_lshl_add_u64 v[58:59], s[8:9], 0, v[58:59]
	s_waitcnt lgkmcnt(1)
	v_add_f32_e32 v60, v60, v61
	ds_bpermute_b32 v61, v49, v60
	s_waitcnt lgkmcnt(1)
	v_add_f32_e32 v36, v36, v62
	global_load_dwordx4 v[32:35], v[42:43], off
	ds_bpermute_b32 v51, v70, v36
	s_waitcnt lgkmcnt(1)
	v_add_f32_e32 v62, v60, v61
	ds_bpermute_b32 v63, v70, v62
	v_lshl_add_u64 v[60:61], v[58:59], 0, s[12:13]
	v_lshl_add_u64 v[58:59], v[58:59], 0, s[14:15]
	v_lshl_add_u64 v[64:65], v[58:59], 0, v[52:53]
	s_waitcnt lgkmcnt(1)
	v_add_f32_e32 v36, v36, v51
	s_waitcnt lgkmcnt(0)
	v_add_f32_e32 v66, v62, v63
	v_lshl_add_u64 v[62:63], v[60:61], 0, v[52:53]
	global_load_dwordx4 v[76:79], v[62:63], off
	global_load_dwordx4 v[80:83], v[64:65], off
	global_load_dwordx4 v[84:87], v[42:43], off offset:1024
	global_load_dwordx4 v[96:99], v[62:63], off offset:1024
	global_load_dwordx4 v[108:111], v[64:65], off offset:1024
	global_load_dwordx4 v[88:91], v[42:43], off offset:2048
	global_load_dwordx4 v[100:103], v[62:63], off offset:2048
	global_load_dwordx4 v[112:115], v[64:65], off offset:2048
	global_load_dwordx4 v[92:95], v[42:43], off offset:3072
	global_load_dwordx4 v[104:107], v[62:63], off offset:3072
	global_load_dwordx4 v[116:119], v[64:65], off offset:3072
	ds_bpermute_b32 v51, v71, v36
	ds_bpermute_b32 v67, v71, v66
	s_waitcnt lgkmcnt(1)
	v_add_f32_e32 v36, v36, v51
	ds_bpermute_b32 v51, v72, v36
	s_waitcnt lgkmcnt(1)
	v_add_f32_e32 v66, v66, v67
	ds_bpermute_b32 v67, v72, v66
	s_waitcnt lgkmcnt(1)
	v_add_f32_e32 v36, v36, v51
	v_fmamk_f32 v36, v36, 0x3a800000, v73
	v_mul_f32_e32 v51, 0x4f800000, v36
	v_cmp_gt_f32_e32 vcc, s3, v36
	s_waitcnt lgkmcnt(0)
	v_add_f32_e32 v62, v66, v67
	v_cndmask_b32_e32 v36, v36, v51, vcc
	v_fmamk_f32 v51, v62, 0x3a800000, v73
	v_sqrt_f32_e32 v62, v36
	v_mul_f32_e32 v63, 0x4f800000, v51
	v_cmp_gt_f32_e64 s[4:5], s3, v51
	v_add_u32_e32 v64, -1, v62
	v_cndmask_b32_e64 v51, v51, v63, s[4:5]
	v_sqrt_f32_e32 v63, v51
	v_add_u32_e32 v65, 1, v62
	v_fma_f32 v66, -v64, v62, v36
	v_fma_f32 v67, -v65, v62, v36
	v_cmp_ge_f32_e64 s[6:7], 0, v66
	v_add_u32_e32 v66, 1, v63
	s_nop 0
	v_cndmask_b32_e64 v62, v62, v64, s[6:7]
	v_add_u32_e32 v64, -1, v63
	v_cmp_lt_f32_e64 s[6:7], 0, v67
	v_fma_f32 v67, -v66, v63, v51
	s_nop 0
	v_cndmask_b32_e64 v62, v62, v65, s[6:7]
	v_fma_f32 v65, -v64, v63, v51
	v_mul_f32_e32 v68, 0x37800000, v62
	v_cmp_ge_f32_e64 s[6:7], 0, v65
	v_cndmask_b32_e32 v62, v62, v68, vcc
	v_cmp_lt_f32_e32 vcc, 0, v67
	v_cndmask_b32_e64 v63, v63, v64, s[6:7]
	s_nop 0
	v_cndmask_b32_e32 v63, v63, v66, vcc
	v_cmp_class_f32_e32 vcc, v36, v74
	s_nop 1
	v_cndmask_b32_e32 v36, v62, v36, vcc
	v_div_scale_f32 v64, s[6:7], v36, v36, 1.0
	v_rcp_f32_e32 v65, v64
	v_mul_f32_e32 v62, 0x37800000, v63
	v_cndmask_b32_e64 v62, v63, v62, s[4:5]
	v_div_scale_f32 v66, vcc, 1.0, v36, 1.0
	v_fma_f32 v63, -v64, v65, 1.0
	v_fmac_f32_e32 v65, v63, v65
	v_mul_f32_e32 v63, v66, v65
	v_cmp_class_f32_e64 s[4:5], v51, v74
	v_fma_f32 v67, -v64, v63, v66
	v_fmac_f32_e32 v63, v67, v65
	v_cndmask_b32_e64 v51, v62, v51, s[4:5]
	v_div_scale_f32 v62, s[4:5], v51, v51, 1.0
	v_fma_f32 v64, -v64, v63, v66
	v_rcp_f32_e32 v66, v62
	v_div_fmas_f32 v63, v64, v65, v63
	v_div_fixup_f32 v68, v63, v36, 1.0
	v_fma_f32 v36, -v62, v66, 1.0
	v_fmac_f32_e32 v66, v36, v66
	v_div_scale_f32 v36, vcc, 1.0, v51, 1.0
	v_mul_f32_e32 v63, v36, v66
	v_fma_f32 v64, -v62, v63, v36
	v_fmac_f32_e32 v63, v64, v66
	v_fma_f32 v36, -v62, v63, v36
	v_div_fmas_f32 v36, v36, v66, v63
	v_div_fixup_f32 v64, v36, v51, 1.0
	v_lshlrev_b64 v[124:125], 11, v[54:55]
	v_lshlrev_b64 v[126:127], 11, v[56:57]
	v_mov_b32_e32 v120, v68
	v_mov_b32_e32 v122, v64
	v_lshl_add_u64 v[124:125], v[40:41], 0, v[124:125]
	v_lshl_add_u64 v[126:127], v[40:41], 0, v[126:127]
	s_waitcnt vmcnt(0)
	v_pk_add_f32 v[76:77], v[76:77], 1.0 op_sel_hi:[1,0]
	v_pk_add_f32 v[78:79], v[78:79], 1.0 op_sel_hi:[1,0]
	v_pk_mul_f32 v[28:29], v[28:29], v[120:121] op_sel_hi:[1,0]
	v_pk_mul_f32 v[30:31], v[30:31], v[120:121] op_sel_hi:[1,0]
	v_pk_mul_f32 v[28:29], v[32:33], v[28:29]
	v_pk_mul_f32 v[30:31], v[34:35], v[30:31]
	v_pk_fma_f32 v[28:29], v[76:77], v[28:29], v[80:81]
	v_pk_fma_f32 v[30:31], v[78:79], v[30:31], v[82:83]
	v_cvt_pk_bf16_f32 v28, v28, v29
	v_cvt_pk_bf16_f32 v29, v30, v31
	global_store_dwordx2 v[124:125], v[28:29], off
	v_pk_mul_f32 v[24:25], v[24:25], v[122:123] op_sel_hi:[1,0]
	v_pk_mul_f32 v[26:27], v[26:27], v[122:123] op_sel_hi:[1,0]
	v_pk_mul_f32 v[24:25], v[32:33], v[24:25]
	v_pk_mul_f32 v[26:27], v[34:35], v[26:27]
	v_pk_fma_f32 v[24:25], v[76:77], v[24:25], v[80:81]
	v_pk_fma_f32 v[26:27], v[78:79], v[26:27], v[82:83]
	v_cvt_pk_bf16_f32 v24, v24, v25
	v_cvt_pk_bf16_f32 v25, v26, v27
	global_store_dwordx2 v[126:127], v[24:25], off
	v_pk_add_f32 v[96:97], v[96:97], 1.0 op_sel_hi:[1,0]
	v_pk_add_f32 v[98:99], v[98:99], 1.0 op_sel_hi:[1,0]
	v_pk_mul_f32 v[20:21], v[20:21], v[120:121] op_sel_hi:[1,0]
	v_pk_mul_f32 v[22:23], v[22:23], v[120:121] op_sel_hi:[1,0]
	v_pk_mul_f32 v[20:21], v[84:85], v[20:21]
	v_pk_mul_f32 v[22:23], v[86:87], v[22:23]
	v_pk_fma_f32 v[20:21], v[96:97], v[20:21], v[108:109]
	v_pk_fma_f32 v[22:23], v[98:99], v[22:23], v[110:111]
	v_cvt_pk_bf16_f32 v20, v20, v21
	v_cvt_pk_bf16_f32 v21, v22, v23
	global_store_dwordx2 v[124:125], v[20:21], off offset:512
	v_pk_mul_f32 v[16:17], v[16:17], v[122:123] op_sel_hi:[1,0]
	v_pk_mul_f32 v[18:19], v[18:19], v[122:123] op_sel_hi:[1,0]
	v_pk_mul_f32 v[16:17], v[84:85], v[16:17]
	v_pk_mul_f32 v[18:19], v[86:87], v[18:19]
	v_pk_fma_f32 v[16:17], v[96:97], v[16:17], v[108:109]
	v_pk_fma_f32 v[18:19], v[98:99], v[18:19], v[110:111]
	v_cvt_pk_bf16_f32 v16, v16, v17
	v_cvt_pk_bf16_f32 v17, v18, v19
	global_store_dwordx2 v[126:127], v[16:17], off offset:512
	v_pk_add_f32 v[100:101], v[100:101], 1.0 op_sel_hi:[1,0]
	v_pk_add_f32 v[102:103], v[102:103], 1.0 op_sel_hi:[1,0]
	v_pk_mul_f32 v[12:13], v[12:13], v[120:121] op_sel_hi:[1,0]
	v_pk_mul_f32 v[14:15], v[14:15], v[120:121] op_sel_hi:[1,0]
	v_pk_mul_f32 v[12:13], v[88:89], v[12:13]
	v_pk_mul_f32 v[14:15], v[90:91], v[14:15]
	v_pk_fma_f32 v[12:13], v[100:101], v[12:13], v[112:113]
	v_pk_fma_f32 v[14:15], v[102:103], v[14:15], v[114:115]
	v_cvt_pk_bf16_f32 v12, v12, v13
	v_cvt_pk_bf16_f32 v13, v14, v15
	global_store_dwordx2 v[124:125], v[12:13], off offset:1024
	v_pk_mul_f32 v[8:9], v[8:9], v[122:123] op_sel_hi:[1,0]
	v_pk_mul_f32 v[10:11], v[10:11], v[122:123] op_sel_hi:[1,0]
	v_pk_mul_f32 v[8:9], v[88:89], v[8:9]
	v_pk_mul_f32 v[10:11], v[90:91], v[10:11]
	v_pk_fma_f32 v[8:9], v[100:101], v[8:9], v[112:113]
	v_pk_fma_f32 v[10:11], v[102:103], v[10:11], v[114:115]
	v_cvt_pk_bf16_f32 v8, v8, v9
	v_cvt_pk_bf16_f32 v9, v10, v11
	global_store_dwordx2 v[126:127], v[8:9], off offset:1024
	v_pk_add_f32 v[104:105], v[104:105], 1.0 op_sel_hi:[1,0]
	v_pk_add_f32 v[106:107], v[106:107], 1.0 op_sel_hi:[1,0]
	v_pk_mul_f32 v[4:5], v[4:5], v[120:121] op_sel_hi:[1,0]
	v_pk_mul_f32 v[6:7], v[6:7], v[120:121] op_sel_hi:[1,0]
	v_pk_mul_f32 v[4:5], v[92:93], v[4:5]
	v_pk_mul_f32 v[6:7], v[94:95], v[6:7]
	v_pk_fma_f32 v[4:5], v[104:105], v[4:5], v[116:117]
	v_pk_fma_f32 v[6:7], v[106:107], v[6:7], v[118:119]
	v_cvt_pk_bf16_f32 v4, v4, v5
	v_cvt_pk_bf16_f32 v5, v6, v7
	global_store_dwordx2 v[124:125], v[4:5], off offset:1536
	v_pk_mul_f32 v[0:1], v[0:1], v[122:123] op_sel_hi:[1,0]
	v_pk_mul_f32 v[2:3], v[2:3], v[122:123] op_sel_hi:[1,0]
	v_pk_mul_f32 v[0:1], v[92:93], v[0:1]
	v_pk_mul_f32 v[2:3], v[94:95], v[2:3]
	v_pk_fma_f32 v[0:1], v[104:105], v[0:1], v[116:117]
	v_pk_fma_f32 v[2:3], v[106:107], v[2:3], v[118:119]
	v_cvt_pk_bf16_f32 v0, v0, v1
	v_cvt_pk_bf16_f32 v1, v2, v3
	global_store_dwordx2 v[126:127], v[0:1], off offset:1536
	s_mov_b64 s[4:5], exec
	s_branch .LBB0_419

.LBB0_1262:
	v_ashrrev_i32_e32 v55, 31, v54
	v_add_u32_e32 v75, s94, v54
	v_lshlrev_b64 v[0:1], 12, v[54:55]
	v_cmp_gt_i32_e32 vcc, s2, v75
	v_lshl_add_u64 v[0:1], v[38:39], 0, v[0:1]
	global_load_dwordx4 v[28:31], v[0:1], off nt
	global_load_dwordx4 v[20:23], v[0:1], off offset:1024 nt
	global_load_dwordx4 v[4:7], v[0:1], off offset:3072 nt
	global_load_dwordx4 v[12:15], v[0:1], off offset:2048 nt
	v_cndmask_b32_e32 v56, v54, v75, vcc
	v_ashrrev_i32_e32 v57, 31, v56
	v_lshlrev_b64 v[0:1], 12, v[56:57]
	v_lshl_add_u64 v[32:33], v[38:39], 0, v[0:1]
	global_load_dwordx4 v[24:27], v[32:33], off nt
	global_load_dwordx4 v[16:19], v[32:33], off offset:1024 nt
	global_load_dwordx4 v[0:3], v[32:33], off offset:3072 nt
	global_load_dwordx4 v[8:11], v[32:33], off offset:2048 nt
	s_waitcnt vmcnt(7)
	v_pk_mul_f32 v[32:33], v[30:31], v[30:31]
	v_pk_mul_f32 v[34:35], v[28:29], v[28:29]
	s_waitcnt vmcnt(6)
	v_pk_mul_f32 v[58:59], v[22:23], v[22:23]
	v_pk_mul_f32 v[60:61], v[20:21], v[20:21]
	s_waitcnt vmcnt(4)
	v_mul_f32_e32 v62, v15, v15
	v_pk_mov_b32 v[64:65], v[34:35], v[32:33] op_sel:[1,0]
	v_mov_b32_e32 v35, v33
	v_pk_mov_b32 v[32:33], v[60:61], v[58:59] op_sel:[1,0]
	v_mov_b32_e32 v61, v59
	v_mul_f32_e32 v78, v7, v7
	v_mul_f32_e32 v36, v13, v13
	v_pk_fma_f32 v[62:63], v[14:15], v[14:15], v[62:63] op_sel_hi:[1,1,0]
	v_pk_add_f32 v[34:35], v[64:65], v[34:35]
	s_waitcnt vmcnt(3)
	v_pk_mul_f32 v[64:65], v[26:27], v[26:27]
	v_pk_mul_f32 v[66:67], v[24:25], v[24:25]
	v_pk_add_f32 v[32:33], v[32:33], v[60:61]
	s_waitcnt vmcnt(2)
	v_pk_mul_f32 v[60:61], v[18:19], v[18:19]
	v_pk_mul_f32 v[68:69], v[16:17], v[16:17]
	v_mul_f32_e32 v51, v4, v4
	v_mul_f32_e32 v77, v5, v5
	v_mul_f32_e32 v76, v6, v6
	v_pk_fma_f32 v[58:59], v[12:13], v[12:13], v[36:37] op_sel_hi:[1,1,0]
	v_mov_b32_e32 v63, v78
	v_pk_mov_b32 v[78:79], v[66:67], v[64:65] op_sel:[1,0]
	v_mov_b32_e32 v67, v65
	v_pk_mov_b32 v[64:65], v[68:69], v[60:61] op_sel:[1,0]
	v_mov_b32_e32 v69, v61
	v_pk_add_f32 v[34:35], v[34:35], v[34:35] op_sel:[0,1] op_sel_hi:[1,0]
	v_pk_add_f32 v[32:33], v[32:33], v[32:33] op_sel:[0,1] op_sel_hi:[1,0]
	v_mov_b32_e32 v59, v76
	s_waitcnt vmcnt(0)
	v_mul_f32_e32 v36, v9, v9
	v_mul_f32_e32 v76, v11, v11
	v_pk_add_f32 v[66:67], v[78:79], v[66:67]
	v_pk_add_f32 v[64:65], v[64:65], v[68:69]
	v_mov_b32_e32 v35, v51
	v_mov_b32_e32 v33, v77
	v_mul_f32_e32 v80, v0, v0
	v_mul_f32_e32 v81, v1, v1
	v_mul_f32_e32 v82, v2, v2
	v_mul_f32_e32 v83, v3, v3
	v_pk_add_f32 v[58:59], v[58:59], v[62:63]
	v_pk_fma_f32 v[60:61], v[8:9], v[8:9], v[36:37] op_sel_hi:[1,1,0]
	v_pk_fma_f32 v[62:63], v[10:11], v[10:11], v[76:77] op_sel_hi:[1,1,0]
	v_pk_add_f32 v[32:33], v[34:35], v[32:33]
	v_pk_add_f32 v[34:35], v[66:67], v[66:67] op_sel:[0,1] op_sel_hi:[1,0]
	v_pk_add_f32 v[64:65], v[64:65], v[64:65] op_sel:[0,1] op_sel_hi:[1,0]
	v_mov_b32_e32 v61, v82
	v_mov_b32_e32 v63, v83
	v_pk_add_f32 v[32:33], v[32:33], v[58:59]
	v_mov_b32_e32 v35, v80
	v_mov_b32_e32 v65, v81
	v_pk_add_f32 v[60:61], v[60:61], v[62:63]
	v_add_f32_e32 v36, v32, v33
	v_pk_add_f32 v[32:33], v[34:35], v[64:65]
	ds_bpermute_b32 v34, v45, v36
	v_pk_add_f32 v[32:33], v[32:33], v[60:61]
	v_ashrrev_i32_e32 v51, 12, v54
	v_add_f32_e32 v32, v32, v33
	ds_bpermute_b32 v33, v45, v32
	s_waitcnt lgkmcnt(1)
	v_add_f32_e32 v36, v36, v34
	ds_bpermute_b32 v58, v47, v36
	v_mul_hi_i32_i24_e32 v59, 0x9000, v51
	s_waitcnt lgkmcnt(1)
	v_add_f32_e32 v60, v32, v33
	ds_bpermute_b32 v61, v47, v60
	s_waitcnt lgkmcnt(1)
	v_add_f32_e32 v36, v36, v58
	ds_bpermute_b32 v62, v49, v36
	v_mul_i32_i24_e32 v58, 0x9000, v51
	v_lshl_add_u64 v[58:59], s[12:13], 0, v[58:59]
	s_waitcnt lgkmcnt(1)
	v_add_f32_e32 v60, v60, v61
	ds_bpermute_b32 v61, v49, v60
	s_waitcnt lgkmcnt(1)
	v_add_f32_e32 v36, v36, v62
	global_load_dwordx4 v[32:35], v[42:43], off
	ds_bpermute_b32 v51, v70, v36
	s_waitcnt lgkmcnt(1)
	v_add_f32_e32 v62, v60, v61
	ds_bpermute_b32 v63, v70, v62
	v_lshl_add_u64 v[60:61], v[58:59], 0, s[14:15]
	v_lshl_add_u64 v[58:59], v[58:59], 0, s[16:17]
	v_lshl_add_u64 v[64:65], v[58:59], 0, v[52:53]
	s_waitcnt lgkmcnt(1)
	v_add_f32_e32 v36, v36, v51
	s_waitcnt lgkmcnt(0)
	v_add_f32_e32 v66, v62, v63
	v_lshl_add_u64 v[62:63], v[60:61], 0, v[52:53]
	global_load_dwordx4 v[76:79], v[62:63], off
	global_load_dwordx4 v[80:83], v[64:65], off
	global_load_dwordx4 v[84:87], v[42:43], off offset:1024
	global_load_dwordx4 v[96:99], v[62:63], off offset:1024
	global_load_dwordx4 v[108:111], v[64:65], off offset:1024
	global_load_dwordx4 v[88:91], v[42:43], off offset:2048
	global_load_dwordx4 v[100:103], v[62:63], off offset:2048
	global_load_dwordx4 v[112:115], v[64:65], off offset:2048
	global_load_dwordx4 v[92:95], v[42:43], off offset:3072
	global_load_dwordx4 v[104:107], v[62:63], off offset:3072
	global_load_dwordx4 v[116:119], v[64:65], off offset:3072
	ds_bpermute_b32 v51, v71, v36
	ds_bpermute_b32 v67, v71, v66
	s_waitcnt lgkmcnt(1)
	v_add_f32_e32 v36, v36, v51
	ds_bpermute_b32 v51, v72, v36
	s_waitcnt lgkmcnt(1)
	v_add_f32_e32 v66, v66, v67
	ds_bpermute_b32 v67, v72, v66
	s_waitcnt lgkmcnt(1)
	v_add_f32_e32 v36, v36, v51
	v_fmamk_f32 v36, v36, 0x3a800000, v73
	v_mul_f32_e32 v51, 0x4f800000, v36
	v_cmp_gt_f32_e32 vcc, s3, v36
	s_waitcnt lgkmcnt(0)
	v_add_f32_e32 v62, v66, v67
	v_cndmask_b32_e32 v36, v36, v51, vcc
	v_fmamk_f32 v51, v62, 0x3a800000, v73
	v_sqrt_f32_e32 v62, v36
	v_mul_f32_e32 v63, 0x4f800000, v51
	v_cmp_gt_f32_e64 s[6:7], s3, v51
	v_add_u32_e32 v64, -1, v62
	v_cndmask_b32_e64 v51, v51, v63, s[6:7]
	v_sqrt_f32_e32 v63, v51
	v_add_u32_e32 v65, 1, v62
	v_fma_f32 v66, -v64, v62, v36
	v_fma_f32 v67, -v65, v62, v36
	v_cmp_ge_f32_e64 s[8:9], 0, v66
	v_add_u32_e32 v66, 1, v63
	s_nop 0
	v_cndmask_b32_e64 v62, v62, v64, s[8:9]
	v_add_u32_e32 v64, -1, v63
	v_cmp_lt_f32_e64 s[8:9], 0, v67
	v_fma_f32 v67, -v66, v63, v51
	s_nop 0
	v_cndmask_b32_e64 v62, v62, v65, s[8:9]
	v_fma_f32 v65, -v64, v63, v51
	v_mul_f32_e32 v68, 0x37800000, v62
	v_cmp_ge_f32_e64 s[8:9], 0, v65
	v_cndmask_b32_e32 v62, v62, v68, vcc
	v_cmp_lt_f32_e32 vcc, 0, v67
	v_cndmask_b32_e64 v63, v63, v64, s[8:9]
	s_nop 0
	v_cndmask_b32_e32 v63, v63, v66, vcc
	v_cmp_class_f32_e32 vcc, v36, v74
	s_nop 1
	v_cndmask_b32_e32 v36, v62, v36, vcc
	v_div_scale_f32 v64, s[8:9], v36, v36, 1.0
	v_rcp_f32_e32 v65, v64
	v_mul_f32_e32 v62, 0x37800000, v63
	v_cndmask_b32_e64 v62, v63, v62, s[6:7]
	v_div_scale_f32 v66, vcc, 1.0, v36, 1.0
	v_fma_f32 v63, -v64, v65, 1.0
	v_fmac_f32_e32 v65, v63, v65
	v_mul_f32_e32 v63, v66, v65
	v_cmp_class_f32_e64 s[6:7], v51, v74
	v_fma_f32 v67, -v64, v63, v66
	v_fmac_f32_e32 v63, v67, v65
	v_cndmask_b32_e64 v51, v62, v51, s[6:7]
	v_div_scale_f32 v62, s[6:7], v51, v51, 1.0
	v_fma_f32 v64, -v64, v63, v66
	v_rcp_f32_e32 v66, v62
	v_div_fmas_f32 v63, v64, v65, v63
	v_div_fixup_f32 v68, v63, v36, 1.0
	v_fma_f32 v36, -v62, v66, 1.0
	v_fmac_f32_e32 v66, v36, v66
	v_div_scale_f32 v36, vcc, 1.0, v51, 1.0
	v_mul_f32_e32 v63, v36, v66
	v_fma_f32 v64, -v62, v63, v36
	v_fmac_f32_e32 v63, v64, v66
	v_fma_f32 v36, -v62, v63, v36
	v_div_fmas_f32 v36, v36, v66, v63
	v_div_fixup_f32 v64, v36, v51, 1.0
	v_lshlrev_b64 v[124:125], 11, v[54:55]
	v_lshlrev_b64 v[126:127], 11, v[56:57]
	v_mov_b32_e32 v120, v68
	v_mov_b32_e32 v122, v64
	v_lshl_add_u64 v[124:125], v[40:41], 0, v[124:125]
	v_lshl_add_u64 v[126:127], v[40:41], 0, v[126:127]
	s_waitcnt vmcnt(0)
	v_pk_add_f32 v[76:77], v[76:77], 1.0 op_sel_hi:[1,0]
	v_pk_add_f32 v[78:79], v[78:79], 1.0 op_sel_hi:[1,0]
	v_pk_mul_f32 v[28:29], v[28:29], v[120:121] op_sel_hi:[1,0]
	v_pk_mul_f32 v[30:31], v[30:31], v[120:121] op_sel_hi:[1,0]
	v_pk_mul_f32 v[28:29], v[32:33], v[28:29]
	v_pk_mul_f32 v[30:31], v[34:35], v[30:31]
	v_pk_fma_f32 v[28:29], v[76:77], v[28:29], v[80:81]
	v_pk_fma_f32 v[30:31], v[78:79], v[30:31], v[82:83]
	v_cvt_pk_bf16_f32 v28, v28, v29
	v_cvt_pk_bf16_f32 v29, v30, v31
	global_store_dwordx2 v[124:125], v[28:29], off
	v_pk_mul_f32 v[24:25], v[24:25], v[122:123] op_sel_hi:[1,0]
	v_pk_mul_f32 v[26:27], v[26:27], v[122:123] op_sel_hi:[1,0]
	v_pk_mul_f32 v[24:25], v[32:33], v[24:25]
	v_pk_mul_f32 v[26:27], v[34:35], v[26:27]
	v_pk_fma_f32 v[24:25], v[76:77], v[24:25], v[80:81]
	v_pk_fma_f32 v[26:27], v[78:79], v[26:27], v[82:83]
	v_cvt_pk_bf16_f32 v24, v24, v25
	v_cvt_pk_bf16_f32 v25, v26, v27
	global_store_dwordx2 v[126:127], v[24:25], off
	v_pk_add_f32 v[96:97], v[96:97], 1.0 op_sel_hi:[1,0]
	v_pk_add_f32 v[98:99], v[98:99], 1.0 op_sel_hi:[1,0]
	v_pk_mul_f32 v[20:21], v[20:21], v[120:121] op_sel_hi:[1,0]
	v_pk_mul_f32 v[22:23], v[22:23], v[120:121] op_sel_hi:[1,0]
	v_pk_mul_f32 v[20:21], v[84:85], v[20:21]
	v_pk_mul_f32 v[22:23], v[86:87], v[22:23]
	v_pk_fma_f32 v[20:21], v[96:97], v[20:21], v[108:109]
	v_pk_fma_f32 v[22:23], v[98:99], v[22:23], v[110:111]
	v_cvt_pk_bf16_f32 v20, v20, v21
	v_cvt_pk_bf16_f32 v21, v22, v23
	global_store_dwordx2 v[124:125], v[20:21], off offset:512
	v_pk_mul_f32 v[16:17], v[16:17], v[122:123] op_sel_hi:[1,0]
	v_pk_mul_f32 v[18:19], v[18:19], v[122:123] op_sel_hi:[1,0]
	v_pk_mul_f32 v[16:17], v[84:85], v[16:17]
	v_pk_mul_f32 v[18:19], v[86:87], v[18:19]
	v_pk_fma_f32 v[16:17], v[96:97], v[16:17], v[108:109]
	v_pk_fma_f32 v[18:19], v[98:99], v[18:19], v[110:111]
	v_cvt_pk_bf16_f32 v16, v16, v17
	v_cvt_pk_bf16_f32 v17, v18, v19
	global_store_dwordx2 v[126:127], v[16:17], off offset:512
	v_pk_add_f32 v[100:101], v[100:101], 1.0 op_sel_hi:[1,0]
	v_pk_add_f32 v[102:103], v[102:103], 1.0 op_sel_hi:[1,0]
	v_pk_mul_f32 v[12:13], v[12:13], v[120:121] op_sel_hi:[1,0]
	v_pk_mul_f32 v[14:15], v[14:15], v[120:121] op_sel_hi:[1,0]
	v_pk_mul_f32 v[12:13], v[88:89], v[12:13]
	v_pk_mul_f32 v[14:15], v[90:91], v[14:15]
	v_pk_fma_f32 v[12:13], v[100:101], v[12:13], v[112:113]
	v_pk_fma_f32 v[14:15], v[102:103], v[14:15], v[114:115]
	v_cvt_pk_bf16_f32 v12, v12, v13
	v_cvt_pk_bf16_f32 v13, v14, v15
	global_store_dwordx2 v[124:125], v[12:13], off offset:1024
	v_pk_mul_f32 v[8:9], v[8:9], v[122:123] op_sel_hi:[1,0]
	v_pk_mul_f32 v[10:11], v[10:11], v[122:123] op_sel_hi:[1,0]
	v_pk_mul_f32 v[8:9], v[88:89], v[8:9]
	v_pk_mul_f32 v[10:11], v[90:91], v[10:11]
	v_pk_fma_f32 v[8:9], v[100:101], v[8:9], v[112:113]
	v_pk_fma_f32 v[10:11], v[102:103], v[10:11], v[114:115]
	v_cvt_pk_bf16_f32 v8, v8, v9
	v_cvt_pk_bf16_f32 v9, v10, v11
	global_store_dwordx2 v[126:127], v[8:9], off offset:1024
	v_pk_add_f32 v[104:105], v[104:105], 1.0 op_sel_hi:[1,0]
	v_pk_add_f32 v[106:107], v[106:107], 1.0 op_sel_hi:[1,0]
	v_pk_mul_f32 v[4:5], v[4:5], v[120:121] op_sel_hi:[1,0]
	v_pk_mul_f32 v[6:7], v[6:7], v[120:121] op_sel_hi:[1,0]
	v_pk_mul_f32 v[4:5], v[92:93], v[4:5]
	v_pk_mul_f32 v[6:7], v[94:95], v[6:7]
	v_pk_fma_f32 v[4:5], v[104:105], v[4:5], v[116:117]
	v_pk_fma_f32 v[6:7], v[106:107], v[6:7], v[118:119]
	v_cvt_pk_bf16_f32 v4, v4, v5
	v_cvt_pk_bf16_f32 v5, v6, v7
	global_store_dwordx2 v[124:125], v[4:5], off offset:1536
	v_pk_mul_f32 v[0:1], v[0:1], v[122:123] op_sel_hi:[1,0]
	v_pk_mul_f32 v[2:3], v[2:3], v[122:123] op_sel_hi:[1,0]
	v_pk_mul_f32 v[0:1], v[92:93], v[0:1]
	v_pk_mul_f32 v[2:3], v[94:95], v[2:3]
	v_pk_fma_f32 v[0:1], v[104:105], v[0:1], v[116:117]
	v_pk_fma_f32 v[2:3], v[106:107], v[2:3], v[118:119]
	v_cvt_pk_bf16_f32 v0, v0, v1
	v_cvt_pk_bf16_f32 v1, v2, v3
	global_store_dwordx2 v[126:127], v[0:1], off offset:1536
	s_mov_b64 s[6:7], exec
	s_branch .LBB0_1261

.LBB0_1470:
	s_or_b64 exec, exec, s[0:1]
	s_waitcnt lgkmcnt(0)
	s_barrier
	v_readlane_b32 s0, v252, 4
	v_ashrrev_i32_e32 v0, 6, v230
	s_mov_b32 s6, 0x10000
	v_add_u32_e32 v44, s0, v0
	v_cmp_gt_i32_e32 vcc, s6, v44
	s_and_saveexec_b64 s[0:1], vcc
	s_cbranch_execz .LBB0_1481
	v_and_b32_e32 v2, 64, v231
	v_add_u32_e32 v2, 64, v2
	v_xor_b32_e32 v3, 1, v231
	v_cmp_lt_i32_e32 vcc, v3, v2
	s_load_dwordx4 s[0:3], s[92:93], 0xc8
	v_and_b32_e32 v0, 63, v230
	v_cndmask_b32_e32 v3, v231, v3, vcc
	v_lshlrev_b32_e32 v52, 2, v3
	v_xor_b32_e32 v3, 2, v231
	v_cmp_lt_i32_e32 vcc, v3, v2
	v_mov_b32_e32 v1, 0
	v_lshlrev_b32_e32 v0, 4, v0
	v_cndmask_b32_e32 v3, v231, v3, vcc
	v_lshlrev_b32_e32 v53, 2, v3
	v_xor_b32_e32 v3, 4, v231
	v_cmp_lt_i32_e32 vcc, v3, v2
	s_waitcnt lgkmcnt(0)
	v_lshl_add_u64 v[36:37], s[2:3], 0, v[0:1]
	v_lshl_add_u64 v[38:39], s[0:1], 0, v[0:1]
	v_cndmask_b32_e32 v3, v231, v3, vcc
	v_lshlrev_b32_e32 v54, 2, v3
	v_xor_b32_e32 v3, 8, v231
	v_cmp_lt_i32_e32 vcc, v3, v2
	s_mov_b64 s[4:5], 0
	v_mov_b32_e32 v58, 0x358637bd
	v_cndmask_b32_e32 v3, v231, v3, vcc
	v_lshlrev_b32_e32 v55, 2, v3
	v_xor_b32_e32 v3, 16, v231
	v_cmp_lt_i32_e32 vcc, v3, v2
	s_mov_b32 s7, 0xf800000
	v_mov_b32_e32 v59, 0x260
	v_cndmask_b32_e32 v3, v231, v3, vcc
	v_lshlrev_b32_e32 v56, 2, v3
	v_xor_b32_e32 v3, 32, v231
	v_cmp_lt_i32_e32 vcc, v3, v2
	s_mov_b32 s8, 0xffff
	s_nop 0
	v_cndmask_b32_e32 v2, v231, v3, vcc
	v_lshlrev_b32_e32 v57, 2, v2
	global_load_dwordx4 v[84:87], v[38:39], off
	global_load_dwordx4 v[88:91], v[38:39], off offset:1024
	global_load_dwordx4 v[92:95], v[38:39], off offset:2048
	global_load_dwordx4 v[96:99], v[38:39], off offset:3072
	s_branch .LBB0_1473

.LBB0_1473:
	v_ashrrev_i32_e32 v45, 31, v44
	v_lshlrev_b64 v[0:1], 12, v[44:45]
	v_add_u32_e32 v45, s94, v44
	v_cmp_gt_i32_e32 vcc, s6, v45
	v_lshl_add_u64 v[40:41], v[36:37], 0, v[0:1]
	global_load_dwordx4 v[28:31], v[40:41], off nt
	global_load_dwordx4 v[16:19], v[40:41], off offset:1024 nt
	global_load_dwordx4 v[0:3], v[40:41], off offset:3072 nt
	global_load_dwordx4 v[12:15], v[40:41], off offset:2048 nt
	v_cndmask_b32_e32 v46, v44, v45, vcc
	v_ashrrev_i32_e32 v47, 31, v46
	v_lshlrev_b64 v[4:5], 12, v[46:47]
	v_lshl_add_u64 v[42:43], v[36:37], 0, v[4:5]
	global_load_dwordx4 v[24:27], v[42:43], off nt
	global_load_dwordx4 v[20:23], v[42:43], off offset:1024 nt
	global_load_dwordx4 v[4:7], v[42:43], off offset:3072 nt
	global_load_dwordx4 v[8:11], v[42:43], off offset:2048 nt
	s_waitcnt vmcnt(7)
	v_pk_mul_f32 v[32:33], v[30:31], v[30:31]
	v_pk_mul_f32 v[34:35], v[28:29], v[28:29]
	s_waitcnt vmcnt(6)
	v_pk_mul_f32 v[48:49], v[18:19], v[18:19]
	v_pk_mul_f32 v[50:51], v[16:17], v[16:17]
	s_waitcnt vmcnt(4)
	v_mul_f32_e32 v60, v13, v13
	v_mul_f32_e32 v62, v15, v15
	v_pk_mov_b32 v[64:65], v[34:35], v[32:33] op_sel:[1,0]
	v_mov_b32_e32 v35, v33
	v_pk_mov_b32 v[32:33], v[50:51], v[48:49] op_sel:[1,0]
	v_mov_b32_e32 v51, v49
	v_pk_fma_f32 v[48:49], v[12:13], v[12:13], v[60:61] op_sel_hi:[1,1,0]
	v_pk_fma_f32 v[60:61], v[14:15], v[14:15], v[62:63] op_sel_hi:[1,1,0]
	v_pk_add_f32 v[34:35], v[64:65], v[34:35]
	s_waitcnt vmcnt(3)
	v_pk_mul_f32 v[62:63], v[26:27], v[26:27]
	v_pk_mul_f32 v[64:65], v[24:25], v[24:25]
	v_pk_add_f32 v[32:33], v[32:33], v[50:51]
	s_waitcnt vmcnt(2)
	v_pk_mul_f32 v[50:51], v[22:23], v[22:23]
	v_pk_mul_f32 v[66:67], v[20:21], v[20:21]
	v_mul_f32_e32 v47, v0, v0
	v_mul_f32_e32 v69, v1, v1
	v_mul_f32_e32 v68, v2, v2
	v_mul_f32_e32 v70, v3, v3
	v_pk_mov_b32 v[72:73], v[64:65], v[62:63] op_sel:[1,0]
	v_mov_b32_e32 v65, v63
	v_pk_mov_b32 v[62:63], v[66:67], v[50:51] op_sel:[1,0]
	v_mov_b32_e32 v67, v51
	v_pk_add_f32 v[34:35], v[34:35], v[34:35] op_sel:[0,1] op_sel_hi:[1,0]
	v_pk_add_f32 v[32:33], v[32:33], v[32:33] op_sel:[0,1] op_sel_hi:[1,0]
	v_mov_b32_e32 v49, v68
	v_mov_b32_e32 v61, v70
	s_waitcnt vmcnt(1)
	v_mul_f32_e32 v71, v4, v4
	s_waitcnt vmcnt(0)
	v_mul_f32_e32 v68, v9, v9
	v_mul_f32_e32 v70, v11, v11
	v_pk_add_f32 v[64:65], v[72:73], v[64:65]
	v_pk_add_f32 v[62:63], v[62:63], v[66:67]
	v_mov_b32_e32 v35, v47
	v_mov_b32_e32 v33, v69
	v_mul_f32_e32 v74, v5, v5
	v_mul_f32_e32 v75, v6, v6
	v_mul_f32_e32 v76, v7, v7
	v_pk_add_f32 v[48:49], v[48:49], v[60:61]
	v_pk_fma_f32 v[50:51], v[8:9], v[8:9], v[68:69] op_sel_hi:[1,1,0]
	v_pk_fma_f32 v[60:61], v[10:11], v[10:11], v[70:71] op_sel_hi:[1,1,0]
	v_pk_add_f32 v[32:33], v[34:35], v[32:33]
	v_pk_add_f32 v[34:35], v[64:65], v[64:65] op_sel:[0,1] op_sel_hi:[1,0]
	v_pk_add_f32 v[62:63], v[62:63], v[62:63] op_sel:[0,1] op_sel_hi:[1,0]
	v_mov_b32_e32 v51, v75
	v_mov_b32_e32 v61, v76
	v_pk_add_f32 v[32:33], v[32:33], v[48:49]
	v_mov_b32_e32 v35, v71
	v_mov_b32_e32 v63, v74
	v_pk_add_f32 v[50:51], v[50:51], v[60:61]
	v_add_f32_e32 v47, v32, v33
	v_pk_add_f32 v[32:33], v[34:35], v[62:63]
	ds_bpermute_b32 v34, v52, v47
	v_pk_add_f32 v[32:33], v[32:33], v[50:51]
	s_waitcnt lgkmcnt(0)
	v_add_f32_e32 v34, v47, v34
	v_add_f32_e32 v32, v32, v33
	ds_bpermute_b32 v33, v52, v32
	ds_bpermute_b32 v35, v53, v34
	s_waitcnt lgkmcnt(1)
	v_add_f32_e32 v32, v32, v33
	ds_bpermute_b32 v33, v53, v32
	s_waitcnt lgkmcnt(1)
	v_add_f32_e32 v34, v34, v35
	ds_bpermute_b32 v35, v54, v34
	s_waitcnt lgkmcnt(1)
	v_add_f32_e32 v32, v32, v33
	ds_bpermute_b32 v33, v54, v32
	s_waitcnt lgkmcnt(1)
	v_add_f32_e32 v47, v34, v35
	ds_bpermute_b32 v48, v55, v47
	s_waitcnt lgkmcnt(1)
	v_add_f32_e32 v49, v32, v33
	ds_bpermute_b32 v50, v55, v49
	s_waitcnt lgkmcnt(1)
	v_add_f32_e32 v47, v47, v48
	ds_bpermute_b32 v48, v56, v47
	s_waitcnt lgkmcnt(1)
	v_add_f32_e32 v49, v49, v50
	ds_bpermute_b32 v50, v56, v49
	s_waitcnt lgkmcnt(1)
	v_add_f32_e32 v47, v47, v48
	ds_bpermute_b32 v48, v57, v47
	s_waitcnt lgkmcnt(1)
	v_add_f32_e32 v49, v49, v50
	ds_bpermute_b32 v50, v57, v49
	s_waitcnt lgkmcnt(1)
	v_add_f32_e32 v47, v47, v48
	v_fmamk_f32 v47, v47, 0x3a800000, v58
	v_mul_f32_e32 v48, 0x4f800000, v47
	v_cmp_gt_f32_e32 vcc, s7, v47
	s_waitcnt lgkmcnt(0)
	v_add_f32_e32 v49, v49, v50
	v_cndmask_b32_e32 v47, v47, v48, vcc
	v_fmamk_f32 v48, v49, 0x3a800000, v58
	v_sqrt_f32_e32 v49, v47
	v_mul_f32_e32 v50, 0x4f800000, v48
	v_cmp_gt_f32_e64 s[0:1], s7, v48
	v_add_u32_e32 v51, -1, v49
	s_nop 0
	v_cndmask_b32_e64 v48, v48, v50, s[0:1]
	v_sqrt_f32_e32 v50, v48
	v_add_u32_e32 v60, 1, v49
	v_fma_f32 v61, -v51, v49, v47
	v_fma_f32 v62, -v60, v49, v47
	v_cmp_ge_f32_e64 s[2:3], 0, v61
	v_add_u32_e32 v61, 1, v50
	s_nop 0
	v_cndmask_b32_e64 v49, v49, v51, s[2:3]
	v_add_u32_e32 v51, -1, v50
	v_cmp_lt_f32_e64 s[2:3], 0, v62
	v_fma_f32 v62, -v61, v50, v48
	s_nop 0
	v_cndmask_b32_e64 v49, v49, v60, s[2:3]
	v_fma_f32 v60, -v51, v50, v48
	v_mul_f32_e32 v63, 0x37800000, v49
	v_cmp_ge_f32_e64 s[2:3], 0, v60
	v_cndmask_b32_e32 v49, v49, v63, vcc
	v_cmp_lt_f32_e32 vcc, 0, v62
	v_cndmask_b32_e64 v50, v50, v51, s[2:3]
	s_nop 0
	v_cndmask_b32_e32 v50, v50, v61, vcc
	v_cmp_class_f32_e32 vcc, v47, v59
	s_nop 1
	v_cndmask_b32_e32 v47, v49, v47, vcc
	v_mul_f32_e32 v49, 0x37800000, v50
	v_div_scale_f32 v51, s[2:3], v47, v47, 1.0
	v_cndmask_b32_e64 v49, v50, v49, s[0:1]
	v_rcp_f32_e32 v50, v51
	v_cmp_class_f32_e64 s[0:1], v48, v59
	v_div_scale_f32 v60, vcc, 1.0, v47, 1.0
	s_nop 0
	v_cndmask_b32_e64 v48, v49, v48, s[0:1]
	v_div_scale_f32 v49, s[0:1], v48, v48, 1.0
	v_rcp_f32_e32 v62, v49
	v_fma_f32 v63, -v51, v50, 1.0
	v_fmac_f32_e32 v50, v63, v50
	v_mul_f32_e32 v63, v60, v50
	v_fma_f32 v65, -v51, v63, v60
	v_fma_f32 v64, -v49, v62, 1.0
	v_fmac_f32_e32 v63, v65, v50
	v_div_scale_f32 v61, s[0:1], 1.0, v48, 1.0
	v_fmac_f32_e32 v62, v64, v62
	v_fma_f32 v51, -v51, v63, v60
	v_mul_f32_e32 v64, v61, v62
	v_div_fmas_f32 v50, v51, v50, v63
	v_div_fixup_f32 v50, v50, v47, 1.0
	v_fma_f32 v47, -v49, v64, v61
	v_fmac_f32_e32 v64, v47, v62
	v_fma_f32 v47, -v49, v64, v61
	s_mov_b64 vcc, s[0:1]
	v_div_fmas_f32 v47, v47, v62, v64
	v_mov_b32_e32 v51, v50
	v_div_fixup_f32 v48, v47, v48, 1.0
	v_mov_b32_e32 v120, v50
	v_mov_b32_e32 v122, v48
	v_pk_mul_f32 v[28:29], v[28:29], v[120:121] op_sel_hi:[1,0]
	v_pk_mul_f32 v[30:31], v[30:31], v[120:121] op_sel_hi:[1,0]
	v_pk_mul_f32 v[28:29], v[84:85], v[28:29]
	v_pk_mul_f32 v[30:31], v[86:87], v[30:31]
	global_store_dwordx4 v[40:41], v[28:31], off nt
	v_pk_mul_f32 v[24:25], v[24:25], v[122:123] op_sel_hi:[1,0]
	v_pk_mul_f32 v[26:27], v[26:27], v[122:123] op_sel_hi:[1,0]
	v_pk_mul_f32 v[24:25], v[84:85], v[24:25]
	v_pk_mul_f32 v[26:27], v[86:87], v[26:27]
	global_store_dwordx4 v[42:43], v[24:27], off nt
	v_pk_mul_f32 v[16:17], v[16:17], v[120:121] op_sel_hi:[1,0]
	v_pk_mul_f32 v[18:19], v[18:19], v[120:121] op_sel_hi:[1,0]
	v_pk_mul_f32 v[16:17], v[88:89], v[16:17]
	v_pk_mul_f32 v[18:19], v[90:91], v[18:19]
	global_store_dwordx4 v[40:41], v[16:19], off offset:1024 nt
	v_pk_mul_f32 v[20:21], v[20:21], v[122:123] op_sel_hi:[1,0]
	v_pk_mul_f32 v[22:23], v[22:23], v[122:123] op_sel_hi:[1,0]
	v_pk_mul_f32 v[20:21], v[88:89], v[20:21]
	v_pk_mul_f32 v[22:23], v[90:91], v[22:23]
	global_store_dwordx4 v[42:43], v[20:23], off offset:1024 nt
	v_pk_mul_f32 v[12:13], v[12:13], v[120:121] op_sel_hi:[1,0]
	v_pk_mul_f32 v[14:15], v[14:15], v[120:121] op_sel_hi:[1,0]
	v_pk_mul_f32 v[12:13], v[92:93], v[12:13]
	v_pk_mul_f32 v[14:15], v[94:95], v[14:15]
	global_store_dwordx4 v[40:41], v[12:15], off offset:2048 nt
	v_pk_mul_f32 v[8:9], v[8:9], v[122:123] op_sel_hi:[1,0]
	v_pk_mul_f32 v[10:11], v[10:11], v[122:123] op_sel_hi:[1,0]
	v_pk_mul_f32 v[8:9], v[92:93], v[8:9]
	v_pk_mul_f32 v[10:11], v[94:95], v[10:11]
	global_store_dwordx4 v[42:43], v[8:11], off offset:2048 nt
	v_pk_mul_f32 v[0:1], v[0:1], v[120:121] op_sel_hi:[1,0]
	v_pk_mul_f32 v[2:3], v[2:3], v[120:121] op_sel_hi:[1,0]
	v_pk_mul_f32 v[0:1], v[96:97], v[0:1]
	v_pk_mul_f32 v[2:3], v[98:99], v[2:3]
	global_store_dwordx4 v[40:41], v[0:3], off offset:3072 nt
	v_pk_mul_f32 v[4:5], v[4:5], v[122:123] op_sel_hi:[1,0]
	v_pk_mul_f32 v[6:7], v[6:7], v[122:123] op_sel_hi:[1,0]
	v_pk_mul_f32 v[4:5], v[96:97], v[4:5]
	v_pk_mul_f32 v[6:7], v[98:99], v[6:7]
	global_store_dwordx4 v[42:43], v[4:7], off offset:3072 nt
	s_mov_b64 s[0:1], exec
	s_branch .LBB0_1472
